# v41 + M4 kv_b epilogue: the k_pe input pairs of rows 1..7 prefetched at the head of the second row loop (7 serial round trips per tile removed)
# speedup vs baseline: 1.0091x; 1.0091x over previous
; __device__ __forceinline__ unsigned cvt_pk_bf16(float lo, float hi) { unsigned r; asm volatile("v_cvt_pk_bf16_f32 %0, %1, %2" : "=v"(r) : "v"(lo), "v"(hi)); return r; }
; #define PG8_LAS __attribute__((address_space(3)))
;     __device__ __forceinline__ void operator()(const f32x4 (&acc)[2][2][4][2], const Unit& u, int wr, int wc, int fr, int fq) const {
;     ...
; #pragma unroll
;         for (int ai = 0; ai < 2; ++ai)
; #pragma unroll
;             for (int m = 0; m < 4; ++m) { const int row = row0 + ai * HALF + m * 16;
;                 const f32x4 p = *(const PG8_LAS f32x4*)(scr + (ai * HALF + rowl0 + m * 16) * 4);
;                 const float rinv = __builtin_amdgcn_rsqf((((p[0] + p[1]) + (p[2] + p[3])) + ssq_kp[row]) * (1.f / QKD) + EPS), ks = rl[ai][m] * rinv;
;                 bf16_t* kvp = KV + (size_t)row * (NH * 256) + h * 256 + colk;
;                 { const f32x4 k0 = acc[ai][0][m][0] * ks * g0, k1 = acc[ai][0][m][1] * ks * g1;
;                   u32x4 w; w.x = cvt_pk_bf16(k0[0], k0[1]); w.y = cvt_pk_bf16(k0[2], k0[3]); w.z = cvt_pk_bf16(k1[0], k1[1]); w.w = cvt_pk_bf16(k1[2], k1[3]); *(u32x4*)kvp = w; }
;                 { const f32x4 v0 = acc[ai][1][m][0] * rl[ai][m], v1 = acc[ai][1][m][1] * rl[ai][m];
;                   u32x4 w; w.x = cvt_pk_bf16(v0[0], v0[1]); w.y = cvt_pk_bf16(v0[2], v0[3]); w.z = cvt_pk_bf16(v1[0], v1[1]); w.w = cvt_pk_bf16(v1[2], v1[3]); *(u32x4*)(kvp + 128) = w; }
;                 const float* kp = QK + (size_t)row * NQKVA + (QLORA + KVLORA) + dA;
;                 const f32x2 ya = *(const f32x2*)kp * rinv * ga, yb = *(const f32x2*)(kp + 16) * rinv * gb;
;                 f32x2 cs = (f32x2){1.f, 1.f}, sn = (f32x2){0.f, 0.f};
;                 if (row < MLAT) { const int s = row & (SEQ - 1), pos = wc < 2 ? (s >> 6) : (s & 63); cs = *(const f32x2*)(rope + pos * 16 + ff); sn = *(const f32x2*)(rope + 1024 + pos * 16 + ff); }
;                 const f32x2 za = ya * cs - yb * sn, zb = yb * cs + ya * sn;
;                 bf16_t* pe = KPE + (size_t)row * (NH * QKR) + h * QKR + dA;
;                 *(unsigned*)pe = cvt_pk_bf16(za.x, za.y); *(unsigned*)(pe + 16) = cvt_pk_bf16(zb.x, zb.y); }
.LBB0_1356:
	s_or_b64 exec, exec, s[36:37]
	s_waitcnt lgkmcnt(0)
	s_barrier
	v_lshl_add_u64 v[178:179], v[166:167], 2, s[20:21]
	s_waitcnt lgkmcnt(0)
	global_load_dwordx4 v[64:67], v[148:149], off offset:16
	global_load_dwordx4 v[68:71], v[148:149], off
	global_load_dwordx2 v[156:157], v[150:151], off offset:512
	global_load_dwordx2 v[158:159], v[150:151], off offset:576
	global_load_dword v165, v[178:179], off
	v_add_u32_e32 v163, 0, v199
	v_add_u32_e32 v163, 0x20000, v163
	ds_read_b128 v[202:205], v163
	s_lshl_b32 s36, s38, 8
	v_lshlrev_b64 v[176:177], 12, v[166:167]
	s_ashr_i32 s37, s36, 31
	v_lshl_add_u64 v[176:177], s[14:15], 0, v[176:177]
	s_waitcnt lgkmcnt(0)
	v_mov_b32_e32 v174, v203
	v_mov_b32_e32 v175, v204
	v_mov_b32_e32 v203, v205
	v_pk_add_f32 v[174:175], v[174:175], v[202:203]
	v_lshl_add_u64 v[176:177], s[36:37], 1, v[176:177]
	v_add_f32_e32 v163, v174, v175
	v_lshl_add_u64 v[176:177], v[176:177], 0, v[172:173]
	v_mov_b32_e32 v185, v184
	v_pk_mul_f32 v[124:125], v[124:125], v[184:185]
	v_lshrrev_b32_e32 v161, 6, v166
	v_cmp_gt_i32_e32 vcc, s83, v166
	s_waitcnt vmcnt(0)
	v_add_f32_e32 v163, v165, v163
	v_fmamk_f32 v163, v163, 0x3baaaaab, v189
	v_rsq_f32_e32 v186, v163
	s_nop 0
	v_mul_f32_e32 v174, v184, v186
	v_pk_mul_f32 v[132:133], v[132:133], v[174:175] op_sel_hi:[1,0]
	v_pk_mul_f32 v[134:135], v[134:135], v[174:175] op_sel_hi:[1,0]
	v_pk_mul_f32 v[128:129], v[128:129], v[174:175] op_sel_hi:[1,0]
	v_pk_mul_f32 v[130:131], v[130:131], v[174:175] op_sel_hi:[1,0]
	v_pk_mul_f32 v[134:135], v[70:71], v[134:135]
	v_pk_mul_f32 v[132:133], v[68:69], v[132:133]
	v_pk_mul_f32 v[174:175], v[66:67], v[130:131]
	v_pk_mul_f32 v[130:131], v[64:65], v[128:129]
	v_cvt_pk_bf16_f32 v128, v132, v133
	v_cvt_pk_bf16_f32 v129, v134, v135
	s_nop 0
	v_cvt_pk_bf16_f32 v130, v130, v131
	v_cvt_pk_bf16_f32 v131, v174, v175
	global_store_dwordx4 v[176:177], v[128:131], off
	s_nop 1
	v_mov_b32_e32 v128, v184
	v_mov_b32_e32 v129, v184
	v_pk_mul_f32 v[126:127], v[126:127], v[128:129]
	v_pk_mul_f32 v[128:129], v[122:123], v[128:129]
	v_pk_mul_f32 v[122:123], v[120:121], v[184:185]
	v_cvt_pk_bf16_f32 v120, v124, v125
	v_cvt_pk_bf16_f32 v121, v126, v127
	v_mov_b32_e32 v124, 0
	v_cvt_pk_bf16_f32 v122, v122, v123
	v_cvt_pk_bf16_f32 v123, v128, v129
	global_store_dwordx4 v[176:177], v[120:123], off offset:256
	v_mov_b32_e32 v128, 1.0
	v_mov_b32_e32 v129, 1.0
	v_mad_i64_i32 v[120:121], s[40:41], v166, s89, v[154:155]
	s_mov_b64 s[40:41], 0xc000
	v_lshl_add_u64 v[174:175], v[120:121], 0, s[40:41]
	global_load_dwordx2 v[176:177], v[174:175], off offset:2560
	global_load_dwordx2 v[208:209], v[174:175], off offset:2624
	s_mov_b64 s[40:41], 0x18000
	v_lshl_add_u64 v[174:175], v[120:121], 0, s[40:41]
	global_load_dwordx2 v[184:185], v[174:175], off offset:2560
	global_load_dwordx2 v[210:211], v[174:175], off offset:2624
	s_mov_b64 s[40:41], 0x24000
	v_lshl_add_u64 v[174:175], v[120:121], 0, s[40:41]
	global_load_dwordx2 v[192:193], v[174:175], off offset:2560
	global_load_dwordx2 v[212:213], v[174:175], off offset:2624
	s_mov_b64 s[40:41], 0x60000
	v_lshl_add_u64 v[174:175], v[120:121], 0, s[40:41]
	global_load_dwordx2 v[194:195], v[174:175], off offset:2560
	global_load_dwordx2 v[214:215], v[174:175], off offset:2624
	s_mov_b64 s[40:41], 0x6c000
	v_lshl_add_u64 v[174:175], v[120:121], 0, s[40:41]
	global_load_dwordx2 v[202:203], v[174:175], off offset:2560
	global_load_dwordx2 v[216:217], v[174:175], off offset:2624
	s_mov_b64 s[40:41], 0x78000
	v_lshl_add_u64 v[174:175], v[120:121], 0, s[40:41]
	global_load_dwordx2 v[204:205], v[174:175], off offset:2560
	global_load_dwordx2 v[218:219], v[174:175], off offset:2624
	s_mov_b64 s[40:41], 0x84000
	v_lshl_add_u64 v[174:175], v[120:121], 0, s[40:41]
	global_load_dwordx2 v[206:207], v[174:175], off offset:2560
	global_load_dwordx2 v[220:221], v[174:175], off offset:2624
	global_load_dwordx2 v[126:127], v[120:121], off offset:2560
	s_nop 0
	global_load_dwordx2 v[120:121], v[120:121], off offset:2624
	v_mov_b32_e32 v122, 1.0
	v_mov_b32_e32 v130, 0
	v_mov_b32_e32 v131, 0
	s_and_saveexec_b64 s[40:41], vcc
	s_cbranch_execz .LBB0_1358
	v_cndmask_b32_e64 v123, v145, v161, s[8:9]
	v_lshlrev_b32_e32 v123, 6, v123
	v_and_b32_e32 v128, 0xfc0, v123
	v_mov_b32_e32 v129, v173
	v_lshl_add_u64 v[130:131], v[146:147], 0, v[128:129]
	v_lshl_add_u64 v[132:133], v[152:153], 0, v[128:129]
	global_load_dwordx2 v[128:129], v[130:131], off
	s_nop 0
	global_load_dwordx2 v[130:131], v[132:133], off
; __device__ __forceinline__ unsigned cvt_pk_bf16(float lo, float hi) { unsigned r; asm volatile("v_cvt_pk_bf16_f32 %0, %1, %2" : "=v"(r) : "v"(lo), "v"(hi)); return r; }
; #define PG8_LAS __attribute__((address_space(3)))
;     __device__ __forceinline__ void operator()(const f32x4 (&acc)[2][2][4][2], const Unit& u, int wr, int wc, int fr, int fq) const {
;     ...
; #pragma unroll
;         for (int ai = 0; ai < 2; ++ai)
; #pragma unroll
;             for (int m = 0; m < 4; ++m) { const int row = row0 + ai * HALF + m * 16;
;                 const f32x4 p = *(const PG8_LAS f32x4*)(scr + (ai * HALF + rowl0 + m * 16) * 4);
;                 const float rinv = __builtin_amdgcn_rsqf((((p[0] + p[1]) + (p[2] + p[3])) + ssq_kp[row]) * (1.f / QKD) + EPS), ks = rl[ai][m] * rinv;
;                 bf16_t* kvp = KV + (size_t)row * (NH * 256) + h * 256 + colk;
;                 { const f32x4 k0 = acc[ai][0][m][0] * ks * g0, k1 = acc[ai][0][m][1] * ks * g1;
;                   u32x4 w; w.x = cvt_pk_bf16(k0[0], k0[1]); w.y = cvt_pk_bf16(k0[2], k0[3]); w.z = cvt_pk_bf16(k1[0], k1[1]); w.w = cvt_pk_bf16(k1[2], k1[3]); *(u32x4*)kvp = w; }
;                 { const f32x4 v0 = acc[ai][1][m][0] * rl[ai][m], v1 = acc[ai][1][m][1] * rl[ai][m];
;                   u32x4 w; w.x = cvt_pk_bf16(v0[0], v0[1]); w.y = cvt_pk_bf16(v0[2], v0[3]); w.z = cvt_pk_bf16(v1[0], v1[1]); w.w = cvt_pk_bf16(v1[2], v1[3]); *(u32x4*)(kvp + 128) = w; }
;                 const float* kp = QK + (size_t)row * NQKVA + (QLORA + KVLORA) + dA;
;                 const f32x2 ya = *(const f32x2*)kp * rinv * ga, yb = *(const f32x2*)(kp + 16) * rinv * gb;
;                 f32x2 cs = (f32x2){1.f, 1.f}, sn = (f32x2){0.f, 0.f};
;                 if (row < MLAT) { const int s = row & (SEQ - 1), pos = wc < 2 ? (s >> 6) : (s & 63); cs = *(const f32x2*)(rope + pos * 16 + ff); sn = *(const f32x2*)(rope + 1024 + pos * 16 + ff); }
;                 const f32x2 za = ya * cs - yb * sn, zb = yb * cs + ya * sn;
;                 bf16_t* pe = KPE + (size_t)row * (NH * QKR) + h * QKR + dA;
;                 *(unsigned*)pe = cvt_pk_bf16(za.x, za.y); *(unsigned*)(pe + 16) = cvt_pk_bf16(zb.x, zb.y); }
.LBB0_1358:
	s_or_b64 exec, exec, s[40:41]
	s_waitcnt vmcnt(0)
	v_pk_mul_f32 v[120:121], v[186:187], v[120:121] op_sel_hi:[0,1]
	v_pk_mul_f32 v[126:127], v[186:187], v[126:127] op_sel_hi:[0,1]
	v_pk_mul_f32 v[120:121], v[158:159], v[120:121]
	v_pk_mul_f32 v[126:127], v[156:157], v[126:127]
	v_pk_mul_f32 v[132:133], v[120:121], v[130:131]
	s_lshl_b32 s38, s38, 6
	v_pk_fma_f32 v[132:133], v[126:127], v[128:129], v[132:133] neg_lo:[0,0,1] neg_hi:[0,0,1]
	v_pk_mul_f32 v[126:127], v[126:127], v[130:131]
	s_ashr_i32 s39, s38, 31
	v_pk_fma_f32 v[126:127], v[120:121], v[128:129], v[126:127]
	v_lshlrev_b64 v[120:121], 10, v[166:167]
	v_lshl_add_u64 v[120:121], s[16:17], 0, v[120:121]
	v_lshl_add_u64 v[128:129], s[38:39], 1, v[120:121]
	v_lshlrev_b32_e32 v120, 1, v144
	v_mov_b32_e32 v121, v173
	v_lshl_add_u64 v[128:129], v[128:129], 0, v[120:121]
	v_cvt_pk_bf16_f32 v123, v132, v133
	s_add_i32 s27, 0, 0x20000
	global_store_dword v[128:129], v123, off
	v_cvt_pk_bf16_f32 v123, v126, v127
	global_store_dword v[128:129], v123, off offset:32
	v_add_u32_e32 v129, s27, v199
	ds_read_b128 v[130:133], v129 offset:256
	v_or_b32_e32 v126, 16, v166
	v_ashrrev_i32_e32 v127, 31, v126
	v_mov_b32_e32 v183, v182
	v_pk_mul_f32 v[108:109], v[108:109], v[182:183]
	s_waitcnt lgkmcnt(0)
	v_mov_b32_e32 v134, v131
	v_mov_b32_e32 v135, v132
	v_mov_b32_e32 v131, v133
	v_pk_add_f32 v[130:131], v[134:135], v[130:131]
	v_lshlrev_b64 v[132:133], 12, v[126:127]
	v_add_f32_e32 v123, v130, v131
	v_lshl_add_u64 v[130:131], v[126:127], 2, s[20:21]
	global_load_dword v125, v[130:131], off
	v_lshl_add_u64 v[132:133], s[14:15], 0, v[132:133]
	v_lshl_add_u64 v[132:133], s[36:37], 1, v[132:133]
	v_lshl_add_u64 v[132:133], v[132:133], 0, v[172:173]
	v_cmp_gt_i32_e32 vcc, s83, v126
	s_waitcnt vmcnt(0)
	v_add_f32_e32 v123, v125, v123
	v_fmamk_f32 v123, v123, 0x3baaaaab, v189
	v_rsq_f32_e32 v128, v123
	v_mov_b32_e32 v123, 1.0
	v_mov_b32_e32 v125, 0
	v_mul_f32_e32 v130, v182, v128
	v_pk_mul_f32 v[116:117], v[116:117], v[130:131] op_sel_hi:[1,0]
	v_pk_mul_f32 v[118:119], v[118:119], v[130:131] op_sel_hi:[1,0]
	v_pk_mul_f32 v[112:113], v[112:113], v[130:131] op_sel_hi:[1,0]
	v_pk_mul_f32 v[114:115], v[114:115], v[130:131] op_sel_hi:[1,0]
	v_pk_mul_f32 v[118:119], v[70:71], v[118:119]
	v_pk_mul_f32 v[116:117], v[68:69], v[116:117]
	v_pk_mul_f32 v[130:131], v[66:67], v[114:115]
	v_pk_mul_f32 v[114:115], v[64:65], v[112:113]
	v_cvt_pk_bf16_f32 v112, v116, v117
	v_cvt_pk_bf16_f32 v113, v118, v119
	s_nop 0
	v_cvt_pk_bf16_f32 v114, v114, v115
	v_cvt_pk_bf16_f32 v115, v130, v131
	global_store_dwordx4 v[132:133], v[112:115], off
	s_nop 1
	v_mov_b32_e32 v112, v182
	v_mov_b32_e32 v113, v182
	v_pk_mul_f32 v[110:111], v[110:111], v[112:113]
	v_pk_mul_f32 v[112:113], v[106:107], v[112:113]
	v_pk_mul_f32 v[106:107], v[104:105], v[182:183]
	v_cvt_pk_bf16_f32 v104, v108, v109
	v_cvt_pk_bf16_f32 v105, v110, v111
	s_nop 0
	v_cvt_pk_bf16_f32 v106, v106, v107
	v_cvt_pk_bf16_f32 v107, v112, v113
	global_store_dwordx4 v[132:133], v[104:107], off offset:256
	s_nop 1
	v_mad_i64_i32 v[104:105], s[40:41], v126, s89, v[154:155]
	s_nop 2
	v_mov_b32_e32 v106, v176
	v_mov_b32_e32 v107, v177
	s_nop 0
	s_nop 2
	v_mov_b32_e32 v104, v208
	v_mov_b32_e32 v105, v209
	s_and_saveexec_b64 s[40:41], vcc
	s_cbranch_execz .LBB0_1360
	v_cndmask_b32_e64 v108, v126, v161, s[8:9]
	v_lshlrev_b32_e32 v108, 6, v108
	v_and_b32_e32 v108, 0xfc0, v108
	v_mov_b32_e32 v109, v173
	v_lshl_add_u64 v[110:111], v[146:147], 0, v[108:109]
	v_lshl_add_u64 v[108:109], v[152:153], 0, v[108:109]
	global_load_dwordx2 v[122:123], v[110:111], off
	global_load_dwordx2 v[124:125], v[108:109], off
.LBB0_1360:
	s_or_b64 exec, exec, s[40:41]
	s_waitcnt vmcnt(0)
	v_pk_mul_f32 v[104:105], v[128:129], v[104:105] op_sel_hi:[0,1]
	v_pk_mul_f32 v[106:107], v[128:129], v[106:107] op_sel_hi:[0,1]
	v_pk_mul_f32 v[104:105], v[158:159], v[104:105]
	v_pk_mul_f32 v[106:107], v[156:157], v[106:107]
	v_pk_mul_f32 v[108:109], v[104:105], v[124:125]
	v_mov_b32_e32 v181, v180
	v_pk_fma_f32 v[108:109], v[106:107], v[122:123], v[108:109] neg_lo:[0,0,1] neg_hi:[0,0,1]
	v_pk_mul_f32 v[106:107], v[106:107], v[124:125]
	v_cvt_pk_bf16_f32 v108, v108, v109
	v_pk_mul_f32 v[92:93], v[92:93], v[180:181]
	v_pk_fma_f32 v[104:105], v[104:105], v[122:123], v[106:107]
	v_lshlrev_b64 v[106:107], 10, v[126:127]
	v_lshl_add_u64 v[106:107], s[16:17], 0, v[106:107]
	v_lshl_add_u64 v[106:107], s[38:39], 1, v[106:107]
	v_lshl_add_u64 v[106:107], v[106:107], 0, v[120:121]
	global_store_dword v[106:107], v108, off
	v_cvt_pk_bf16_f32 v104, v104, v105
	global_store_dword v[106:107], v104, off offset:32
	ds_read_b128 v[106:109], v129 offset:512
	v_or_b32_e32 v104, 32, v166
	v_ashrrev_i32_e32 v105, 31, v104
	v_cmp_gt_i32_e32 vcc, s83, v104
	s_waitcnt lgkmcnt(0)
	v_mov_b32_e32 v110, v107
	v_mov_b32_e32 v111, v108
	v_mov_b32_e32 v107, v109
	v_pk_add_f32 v[106:107], v[110:111], v[106:107]
	v_lshlrev_b64 v[110:111], 12, v[104:105]
	v_add_f32_e32 v108, v106, v107
	v_lshl_add_u64 v[106:107], v[104:105], 2, s[20:21]
	global_load_dword v106, v[106:107], off
	v_lshl_add_u64 v[110:111], s[14:15], 0, v[110:111]
	v_lshl_add_u64 v[110:111], s[36:37], 1, v[110:111]
	v_lshl_add_u64 v[110:111], v[110:111], 0, v[172:173]
	s_waitcnt vmcnt(0)
	v_add_f32_e32 v106, v106, v108
	v_fmamk_f32 v106, v106, 0x3baaaaab, v189
	v_rsq_f32_e32 v106, v106
	s_nop 0
	v_mul_f32_e32 v108, v180, v106
	v_pk_mul_f32 v[100:101], v[100:101], v[108:109] op_sel_hi:[1,0]
	v_pk_mul_f32 v[102:103], v[102:103], v[108:109] op_sel_hi:[1,0]
	v_pk_mul_f32 v[96:97], v[96:97], v[108:109] op_sel_hi:[1,0]
	v_pk_mul_f32 v[98:99], v[98:99], v[108:109] op_sel_hi:[1,0]
	v_pk_mul_f32 v[102:103], v[70:71], v[102:103]
	v_pk_mul_f32 v[100:101], v[68:69], v[100:101]
	v_pk_mul_f32 v[108:109], v[66:67], v[98:99]
	v_pk_mul_f32 v[98:99], v[64:65], v[96:97]
	v_cvt_pk_bf16_f32 v96, v100, v101
	v_cvt_pk_bf16_f32 v97, v102, v103
	s_nop 0
	v_cvt_pk_bf16_f32 v98, v98, v99
	v_cvt_pk_bf16_f32 v99, v108, v109
	global_store_dwordx4 v[110:111], v[96:99], off
	s_nop 1
	v_mov_b32_e32 v96, v180
	v_mov_b32_e32 v97, v180
	v_pk_mul_f32 v[94:95], v[94:95], v[96:97]
	v_pk_mul_f32 v[96:97], v[90:91], v[96:97]
	v_pk_mul_f32 v[90:91], v[88:89], v[180:181]
	v_cvt_pk_bf16_f32 v88, v92, v93
	v_cvt_pk_bf16_f32 v89, v94, v95
	v_mov_b32_e32 v98, 0
	v_cvt_pk_bf16_f32 v90, v90, v91
	v_cvt_pk_bf16_f32 v91, v96, v97
	global_store_dwordx4 v[110:111], v[88:91], off offset:256
	v_mov_b32_e32 v96, 1.0
	v_mov_b32_e32 v97, 1.0
	v_mad_i64_i32 v[88:89], s[40:41], v104, s89, v[154:155]
	s_nop 2
	v_mov_b32_e32 v94, v184
	v_mov_b32_e32 v95, v185
	s_nop 2
	v_mov_b32_e32 v92, v210
	v_mov_b32_e32 v93, v211
	v_mov_b32_e32 v90, 0
	v_mov_b32_e32 v88, 1.0
	v_mov_b32_e32 v99, 0
	s_and_saveexec_b64 s[40:41], vcc
	s_cbranch_execz .LBB0_1362
; __device__ __forceinline__ unsigned cvt_pk_bf16(float lo, float hi) { unsigned r; asm volatile("v_cvt_pk_bf16_f32 %0, %1, %2" : "=v"(r) : "v"(lo), "v"(hi)); return r; }
; #define PG8_LAS __attribute__((address_space(3)))
;     __device__ __forceinline__ void operator()(const f32x4 (&acc)[2][2][4][2], const Unit& u, int wr, int wc, int fr, int fq) const {
;     ...
; #pragma unroll
;         for (int ai = 0; ai < 2; ++ai)
; #pragma unroll
;             for (int m = 0; m < 4; ++m) { const int row = row0 + ai * HALF + m * 16;
;                 const f32x4 p = *(const PG8_LAS f32x4*)(scr + (ai * HALF + rowl0 + m * 16) * 4);
;                 const float rinv = __builtin_amdgcn_rsqf((((p[0] + p[1]) + (p[2] + p[3])) + ssq_kp[row]) * (1.f / QKD) + EPS), ks = rl[ai][m] * rinv;
;                 bf16_t* kvp = KV + (size_t)row * (NH * 256) + h * 256 + colk;
;                 { const f32x4 k0 = acc[ai][0][m][0] * ks * g0, k1 = acc[ai][0][m][1] * ks * g1;
;                   u32x4 w; w.x = cvt_pk_bf16(k0[0], k0[1]); w.y = cvt_pk_bf16(k0[2], k0[3]); w.z = cvt_pk_bf16(k1[0], k1[1]); w.w = cvt_pk_bf16(k1[2], k1[3]); *(u32x4*)kvp = w; }
;                 { const f32x4 v0 = acc[ai][1][m][0] * rl[ai][m], v1 = acc[ai][1][m][1] * rl[ai][m];
;                   u32x4 w; w.x = cvt_pk_bf16(v0[0], v0[1]); w.y = cvt_pk_bf16(v0[2], v0[3]); w.z = cvt_pk_bf16(v1[0], v1[1]); w.w = cvt_pk_bf16(v1[2], v1[3]); *(u32x4*)(kvp + 128) = w; }
;                 const float* kp = QK + (size_t)row * NQKVA + (QLORA + KVLORA) + dA;
;                 const f32x2 ya = *(const f32x2*)kp * rinv * ga, yb = *(const f32x2*)(kp + 16) * rinv * gb;
;                 f32x2 cs = (f32x2){1.f, 1.f}, sn = (f32x2){0.f, 0.f};
;                 if (row < MLAT) { const int s = row & (SEQ - 1), pos = wc < 2 ? (s >> 6) : (s & 63); cs = *(const f32x2*)(rope + pos * 16 + ff); sn = *(const f32x2*)(rope + 1024 + pos * 16 + ff); }
;                 const f32x2 za = ya * cs - yb * sn, zb = yb * cs + ya * sn;
;                 bf16_t* pe = KPE + (size_t)row * (NH * QKR) + h * QKR + dA;
;                 *(unsigned*)pe = cvt_pk_bf16(za.x, za.y); *(unsigned*)(pe + 16) = cvt_pk_bf16(zb.x, zb.y); }
	v_cndmask_b32_e64 v89, v104, v161, s[8:9]
	v_lshlrev_b32_e32 v89, 6, v89
	v_and_b32_e32 v96, 0xfc0, v89
	v_mov_b32_e32 v97, v173
	v_lshl_add_u64 v[98:99], v[146:147], 0, v[96:97]
	v_lshl_add_u64 v[100:101], v[152:153], 0, v[96:97]
	global_load_dwordx2 v[96:97], v[98:99], off
	s_nop 0
	global_load_dwordx2 v[98:99], v[100:101], off
.LBB0_1362:
	s_or_b64 exec, exec, s[40:41]
	s_waitcnt vmcnt(0)
	v_pk_mul_f32 v[92:93], v[106:107], v[92:93] op_sel_hi:[0,1]
	v_pk_mul_f32 v[94:95], v[106:107], v[94:95] op_sel_hi:[0,1]
	v_pk_mul_f32 v[92:93], v[158:159], v[92:93]
	v_pk_mul_f32 v[94:95], v[156:157], v[94:95]
	v_pk_mul_f32 v[100:101], v[92:93], v[98:99]
	v_mov_b32_e32 v121, v173
	v_pk_fma_f32 v[100:101], v[94:95], v[96:97], v[100:101] neg_lo:[0,0,1] neg_hi:[0,0,1]
	v_pk_mul_f32 v[94:95], v[94:95], v[98:99]
	v_cvt_pk_bf16_f32 v89, v100, v101
	v_mov_b32_e32 v171, v170
	v_pk_fma_f32 v[92:93], v[92:93], v[96:97], v[94:95]
	v_lshlrev_b64 v[94:95], 10, v[104:105]
	v_lshl_add_u64 v[94:95], s[16:17], 0, v[94:95]
	v_lshl_add_u64 v[94:95], s[38:39], 1, v[94:95]
	v_lshl_add_u64 v[94:95], v[94:95], 0, v[120:121]
	global_store_dword v[94:95], v89, off
	v_cvt_pk_bf16_f32 v89, v92, v93
	global_store_dword v[94:95], v89, off offset:32
	ds_read_b128 v[94:97], v129 offset:768
	v_or_b32_e32 v92, 48, v166
	v_ashrrev_i32_e32 v93, 31, v92
	v_pk_mul_f32 v[76:77], v[76:77], v[170:171]
	v_cmp_gt_i32_e32 vcc, s83, v92
	s_waitcnt lgkmcnt(0)
	v_mov_b32_e32 v98, v95
	v_mov_b32_e32 v99, v96
	v_mov_b32_e32 v95, v97
	v_pk_add_f32 v[94:95], v[98:99], v[94:95]
	v_lshlrev_b64 v[98:99], 12, v[92:93]
	v_add_f32_e32 v89, v94, v95
	v_lshl_add_u64 v[94:95], v[92:93], 2, s[20:21]
	global_load_dword v91, v[94:95], off
	v_lshl_add_u64 v[98:99], s[14:15], 0, v[98:99]
	v_lshl_add_u64 v[98:99], s[36:37], 1, v[98:99]
	v_lshl_add_u64 v[98:99], v[98:99], 0, v[172:173]
	s_waitcnt vmcnt(0)
	v_add_f32_e32 v89, v91, v89
	v_fmamk_f32 v89, v89, 0x3baaaaab, v189
	v_rsq_f32_e32 v94, v89
	v_mov_b32_e32 v89, 1.0
	v_mov_b32_e32 v91, 0
	v_mul_f32_e32 v96, v170, v94
	v_pk_mul_f32 v[84:85], v[84:85], v[96:97] op_sel_hi:[1,0]
	v_pk_mul_f32 v[86:87], v[86:87], v[96:97] op_sel_hi:[1,0]
	v_pk_mul_f32 v[80:81], v[80:81], v[96:97] op_sel_hi:[1,0]
	v_pk_mul_f32 v[82:83], v[82:83], v[96:97] op_sel_hi:[1,0]
	v_pk_mul_f32 v[86:87], v[70:71], v[86:87]
	v_pk_mul_f32 v[84:85], v[68:69], v[84:85]
	v_pk_mul_f32 v[96:97], v[66:67], v[82:83]
	v_pk_mul_f32 v[82:83], v[64:65], v[80:81]
	v_cvt_pk_bf16_f32 v80, v84, v85
	v_cvt_pk_bf16_f32 v81, v86, v87
	s_nop 0
	v_cvt_pk_bf16_f32 v82, v82, v83
	v_cvt_pk_bf16_f32 v83, v96, v97
	global_store_dwordx4 v[98:99], v[80:83], off
	s_nop 1
	v_mov_b32_e32 v80, v170
	v_mov_b32_e32 v81, v170
	v_pk_mul_f32 v[78:79], v[78:79], v[80:81]
	v_pk_mul_f32 v[80:81], v[74:75], v[80:81]
	v_pk_mul_f32 v[74:75], v[72:73], v[170:171]
	v_cvt_pk_bf16_f32 v72, v76, v77
	v_cvt_pk_bf16_f32 v73, v78, v79
	s_nop 0
	v_cvt_pk_bf16_f32 v74, v74, v75
	v_cvt_pk_bf16_f32 v75, v80, v81
	global_store_dwordx4 v[98:99], v[72:75], off offset:256
	s_nop 1
	v_mad_i64_i32 v[72:73], s[40:41], v92, s89, v[154:155]
	s_nop 2
	v_mov_b32_e32 v74, v192
	v_mov_b32_e32 v75, v193
	s_nop 0
	s_nop 2
	v_mov_b32_e32 v72, v212
	v_mov_b32_e32 v73, v213
	s_and_saveexec_b64 s[40:41], vcc
	s_cbranch_execz .LBB0_1364
	v_cndmask_b32_e64 v76, v92, v161, s[8:9]
	v_lshlrev_b32_e32 v76, 6, v76
	v_and_b32_e32 v76, 0xfc0, v76
	v_mov_b32_e32 v77, v173
	v_lshl_add_u64 v[78:79], v[146:147], 0, v[76:77]
	v_lshl_add_u64 v[76:77], v[152:153], 0, v[76:77]
	global_load_dwordx2 v[88:89], v[78:79], off
	global_load_dwordx2 v[90:91], v[76:77], off
.LBB0_1364:
	s_or_b64 exec, exec, s[40:41]
	s_waitcnt vmcnt(0)
	v_pk_mul_f32 v[72:73], v[94:95], v[72:73] op_sel_hi:[0,1]
	v_pk_mul_f32 v[74:75], v[94:95], v[74:75] op_sel_hi:[0,1]
	v_pk_mul_f32 v[72:73], v[158:159], v[72:73]
	v_pk_mul_f32 v[74:75], v[156:157], v[74:75]
	v_pk_mul_f32 v[76:77], v[72:73], v[90:91]
	v_mov_b32_e32 v169, v168
	v_pk_fma_f32 v[76:77], v[74:75], v[88:89], v[76:77] neg_lo:[0,0,1] neg_hi:[0,0,1]
	v_pk_mul_f32 v[74:75], v[74:75], v[90:91]
	v_cvt_pk_bf16_f32 v76, v76, v77
	v_mov_b32_e32 v77, v168
	v_pk_fma_f32 v[72:73], v[72:73], v[88:89], v[74:75]
	v_lshlrev_b64 v[74:75], 10, v[92:93]
	v_lshl_add_u64 v[74:75], s[16:17], 0, v[74:75]
	v_lshl_add_u64 v[74:75], s[38:39], 1, v[74:75]
	v_lshl_add_u64 v[74:75], v[74:75], 0, v[120:121]
	global_store_dword v[74:75], v76, off
	v_cvt_pk_bf16_f32 v86, v72, v73
	global_load_dword v87, v[178:179], off offset:512
	v_mov_b32_e32 v76, v168
	v_pk_mul_f32 v[62:63], v[62:63], v[76:77]
	v_pk_mul_f32 v[76:77], v[54:55], v[76:77]
	v_pk_mul_f32 v[78:79], v[52:53], v[168:169]
	ds_read_b128 v[52:55], v129 offset:2048
	v_add_u32_e32 v72, 0x80, v166
	v_ashrrev_i32_e32 v73, 31, v72
	v_lshlrev_b64 v[82:83], 12, v[72:73]
	global_store_dword v[74:75], v86, off offset:32
	s_waitcnt lgkmcnt(0)
	v_mov_b32_e32 v84, v53
	v_mov_b32_e32 v85, v54
	v_mov_b32_e32 v53, v55
	v_pk_add_f32 v[52:53], v[84:85], v[52:53]
	v_lshl_add_u64 v[82:83], s[14:15], 0, v[82:83]
	v_add_f32_e32 v52, v52, v53
	v_lshl_add_u64 v[54:55], s[36:37], 1, v[82:83]
	v_lshl_add_u64 v[54:55], v[54:55], 0, v[172:173]
	v_pk_mul_f32 v[60:61], v[60:61], v[168:169]
	v_mad_i64_i32 v[80:81], s[40:41], v72, s89, v[154:155]
	s_movk_i32 s27, 0x3f80
	v_cmp_gt_i32_e32 vcc, s27, v166
	s_waitcnt vmcnt(1)
	v_add_f32_e32 v52, v87, v52
	v_fmamk_f32 v52, v52, 0x3baaaaab, v189
	v_rsq_f32_e32 v52, v52
	s_nop 0
	v_mul_f32_e32 v74, v168, v52
	v_pk_mul_f32 v[48:49], v[48:49], v[74:75] op_sel_hi:[1,0]
	v_pk_mul_f32 v[50:51], v[50:51], v[74:75] op_sel_hi:[1,0]
	v_pk_mul_f32 v[56:57], v[56:57], v[74:75] op_sel_hi:[1,0]
	v_pk_mul_f32 v[58:59], v[58:59], v[74:75] op_sel_hi:[1,0]
	v_pk_mul_f32 v[74:75], v[66:67], v[50:51]
	v_pk_mul_f32 v[50:51], v[64:65], v[48:49]
	v_pk_mul_f32 v[58:59], v[70:71], v[58:59]
	v_pk_mul_f32 v[56:57], v[68:69], v[56:57]
	s_nop 0
	v_cvt_pk_bf16_f32 v48, v56, v57
	v_cvt_pk_bf16_f32 v49, v58, v59
	v_cvt_pk_bf16_f32 v50, v50, v51
	v_cvt_pk_bf16_f32 v51, v74, v75
	global_store_dwordx4 v[54:55], v[48:51], off
	v_mov_b32_e32 v58, 1.0
	v_mov_b32_e32 v59, 1.0
	v_cvt_pk_bf16_f32 v48, v60, v61
	v_cvt_pk_bf16_f32 v49, v62, v63
	v_cvt_pk_bf16_f32 v50, v78, v79
	v_cvt_pk_bf16_f32 v51, v76, v77
	global_store_dwordx4 v[54:55], v[48:51], off offset:256
	s_nop 2
	v_mov_b32_e32 v56, v194
	v_mov_b32_e32 v57, v195
	s_nop 0
	s_nop 2
	v_mov_b32_e32 v54, v214
	v_mov_b32_e32 v55, v215
	v_lshrrev_b32_e32 v62, 6, v72
	v_mov_b32_e32 v50, 0
	v_mov_b32_e32 v48, 1.0
	v_mov_b32_e32 v60, 0
	v_mov_b32_e32 v61, 0
	s_and_saveexec_b64 s[40:41], vcc
	s_cbranch_execz .LBB0_1366
	v_cndmask_b32_e64 v49, v145, v62, s[8:9]
	v_lshlrev_b32_e32 v49, 6, v49
	v_and_b32_e32 v58, 0xfc0, v49
	v_mov_b32_e32 v59, v173
	v_lshl_add_u64 v[60:61], v[146:147], 0, v[58:59]
	v_lshl_add_u64 v[74:75], v[152:153], 0, v[58:59]
	global_load_dwordx2 v[58:59], v[60:61], off
	s_nop 0
	global_load_dwordx2 v[60:61], v[74:75], off
; __device__ __forceinline__ unsigned cvt_pk_bf16(float lo, float hi) { unsigned r; asm volatile("v_cvt_pk_bf16_f32 %0, %1, %2" : "=v"(r) : "v"(lo), "v"(hi)); return r; }
; #define PG8_LAS __attribute__((address_space(3)))
;     __device__ __forceinline__ void operator()(const f32x4 (&acc)[2][2][4][2], const Unit& u, int wr, int wc, int fr, int fq) const {
;     ...
;             for (int m = 0; m < 4; ++m) { const int row = row0 + ai * HALF + m * 16;
;                 const f32x4 p = *(const PG8_LAS f32x4*)(scr + (ai * HALF + rowl0 + m * 16) * 4);
;                 const float rinv = __builtin_amdgcn_rsqf((((p[0] + p[1]) + (p[2] + p[3])) + ssq_kp[row]) * (1.f / QKD) + EPS), ks = rl[ai][m] * rinv;
;                 bf16_t* kvp = KV + (size_t)row * (NH * 256) + h * 256 + colk;
;                 { const f32x4 k0 = acc[ai][0][m][0] * ks * g0, k1 = acc[ai][0][m][1] * ks * g1;
;                   u32x4 w; w.x = cvt_pk_bf16(k0[0], k0[1]); w.y = cvt_pk_bf16(k0[2], k0[3]); w.z = cvt_pk_bf16(k1[0], k1[1]); w.w = cvt_pk_bf16(k1[2], k1[3]); *(u32x4*)kvp = w; }
;                 { const f32x4 v0 = acc[ai][1][m][0] * rl[ai][m], v1 = acc[ai][1][m][1] * rl[ai][m];
;                   u32x4 w; w.x = cvt_pk_bf16(v0[0], v0[1]); w.y = cvt_pk_bf16(v0[2], v0[3]); w.z = cvt_pk_bf16(v1[0], v1[1]); w.w = cvt_pk_bf16(v1[2], v1[3]); *(u32x4*)(kvp + 128) = w; }
;                 const float* kp = QK + (size_t)row * NQKVA + (QLORA + KVLORA) + dA;
;                 const f32x2 ya = *(const f32x2*)kp * rinv * ga, yb = *(const f32x2*)(kp + 16) * rinv * gb;
;                 f32x2 cs = (f32x2){1.f, 1.f}, sn = (f32x2){0.f, 0.f};
;                 if (row < MLAT) { const int s = row & (SEQ - 1), pos = wc < 2 ? (s >> 6) : (s & 63); cs = *(const f32x2*)(rope + pos * 16 + ff); sn = *(const f32x2*)(rope + 1024 + pos * 16 + ff); }
;                 const f32x2 za = ya * cs - yb * sn, zb = yb * cs + ya * sn;
;                 bf16_t* pe = KPE + (size_t)row * (NH * QKR) + h * QKR + dA;
;                 *(unsigned*)pe = cvt_pk_bf16(za.x, za.y); *(unsigned*)(pe + 16) = cvt_pk_bf16(zb.x, zb.y); }
.LBB0_1366:
	s_or_b64 exec, exec, s[40:41]
	s_waitcnt vmcnt(1)
	v_pk_mul_f32 v[56:57], v[52:53], v[56:57] op_sel_hi:[0,1]
	s_waitcnt vmcnt(0)
	v_pk_mul_f32 v[52:53], v[52:53], v[54:55] op_sel_hi:[0,1]
	v_pk_mul_f32 v[52:53], v[158:159], v[52:53]
	v_pk_mul_f32 v[56:57], v[156:157], v[56:57]
	v_pk_mul_f32 v[54:55], v[52:53], v[60:61]
	v_mov_b32_e32 v121, v173
	v_pk_fma_f32 v[54:55], v[56:57], v[58:59], v[54:55] neg_lo:[0,0,1] neg_hi:[0,0,1]
	v_pk_mul_f32 v[56:57], v[56:57], v[60:61]
	v_cvt_pk_bf16_f32 v49, v54, v55
	v_mov_b32_e32 v165, v164
	v_pk_fma_f32 v[52:53], v[52:53], v[58:59], v[56:57]
	v_lshlrev_b64 v[56:57], 10, v[72:73]
	v_lshl_add_u64 v[56:57], s[16:17], 0, v[56:57]
	v_lshl_add_u64 v[56:57], s[38:39], 1, v[56:57]
	v_lshl_add_u64 v[56:57], v[56:57], 0, v[120:121]
	global_store_dword v[56:57], v49, off
	v_cvt_pk_bf16_f32 v49, v52, v53
	global_store_dword v[56:57], v49, off offset:32
	ds_read_b128 v[54:57], v129 offset:2304
	v_or_b32_e32 v52, 16, v72
	v_ashrrev_i32_e32 v53, 31, v52
	v_pk_mul_f32 v[36:37], v[36:37], v[164:165]
	v_cmp_gt_i32_e32 vcc, s83, v52
	s_waitcnt lgkmcnt(0)
	v_mov_b32_e32 v58, v55
	v_mov_b32_e32 v59, v56
	v_mov_b32_e32 v55, v57
	v_pk_add_f32 v[54:55], v[58:59], v[54:55]
	v_lshlrev_b64 v[58:59], 12, v[52:53]
	v_add_f32_e32 v49, v54, v55
	v_lshl_add_u64 v[54:55], v[52:53], 2, s[20:21]
	global_load_dword v51, v[54:55], off
	v_lshl_add_u64 v[58:59], s[14:15], 0, v[58:59]
	v_lshl_add_u64 v[58:59], s[36:37], 1, v[58:59]
	v_lshl_add_u64 v[58:59], v[58:59], 0, v[172:173]
	s_waitcnt vmcnt(0)
	v_add_f32_e32 v49, v51, v49
	v_fmamk_f32 v49, v49, 0x3baaaaab, v189
	v_rsq_f32_e32 v54, v49
	v_mov_b32_e32 v49, 1.0
	v_mov_b32_e32 v51, 0
	v_mul_f32_e32 v56, v164, v54
	v_pk_mul_f32 v[44:45], v[44:45], v[56:57] op_sel_hi:[1,0]
	v_pk_mul_f32 v[46:47], v[46:47], v[56:57] op_sel_hi:[1,0]
	v_pk_mul_f32 v[40:41], v[40:41], v[56:57] op_sel_hi:[1,0]
	v_pk_mul_f32 v[42:43], v[42:43], v[56:57] op_sel_hi:[1,0]
	v_pk_mul_f32 v[46:47], v[70:71], v[46:47]
	v_pk_mul_f32 v[44:45], v[68:69], v[44:45]
	v_pk_mul_f32 v[56:57], v[66:67], v[42:43]
	v_pk_mul_f32 v[42:43], v[64:65], v[40:41]
	v_cvt_pk_bf16_f32 v40, v44, v45
	v_cvt_pk_bf16_f32 v41, v46, v47
	s_nop 0
	v_cvt_pk_bf16_f32 v42, v42, v43
	v_cvt_pk_bf16_f32 v43, v56, v57
	global_store_dwordx4 v[58:59], v[40:43], off
	s_nop 1
	v_mov_b32_e32 v40, v164
	v_mov_b32_e32 v41, v164
	v_pk_mul_f32 v[38:39], v[38:39], v[40:41]
	v_pk_mul_f32 v[40:41], v[34:35], v[40:41]
	v_pk_mul_f32 v[34:35], v[32:33], v[164:165]
	v_cvt_pk_bf16_f32 v32, v36, v37
	v_cvt_pk_bf16_f32 v33, v38, v39
	s_nop 0
	v_cvt_pk_bf16_f32 v34, v34, v35
	v_cvt_pk_bf16_f32 v35, v40, v41
	global_store_dwordx4 v[58:59], v[32:35], off offset:256
	s_nop 1
	v_mad_i64_i32 v[32:33], s[40:41], v52, s89, v[154:155]
	s_nop 2
	v_mov_b32_e32 v34, v202
	v_mov_b32_e32 v35, v203
	s_nop 0
	s_nop 2
	v_mov_b32_e32 v32, v216
	v_mov_b32_e32 v33, v217
	s_and_saveexec_b64 s[40:41], vcc
	s_cbranch_execz .LBB0_1368
	v_cndmask_b32_e64 v36, v52, v62, s[8:9]
	v_lshlrev_b32_e32 v36, 6, v36
	v_and_b32_e32 v36, 0xfc0, v36
	v_mov_b32_e32 v37, v173
	v_lshl_add_u64 v[38:39], v[146:147], 0, v[36:37]
	v_lshl_add_u64 v[36:37], v[152:153], 0, v[36:37]
	global_load_dwordx2 v[48:49], v[38:39], off
	global_load_dwordx2 v[50:51], v[36:37], off
; __device__ __forceinline__ unsigned cvt_pk_bf16(float lo, float hi) { unsigned r; asm volatile("v_cvt_pk_bf16_f32 %0, %1, %2" : "=v"(r) : "v"(lo), "v"(hi)); return r; }
; #define PG8_LAS __attribute__((address_space(3)))
;     __device__ __forceinline__ void operator()(const f32x4 (&acc)[2][2][4][2], const Unit& u, int wr, int wc, int fr, int fq) const {
;     ...
;             for (int m = 0; m < 4; ++m) { const int row = row0 + ai * HALF + m * 16;
;                 const f32x4 p = *(const PG8_LAS f32x4*)(scr + (ai * HALF + rowl0 + m * 16) * 4);
;                 const float rinv = __builtin_amdgcn_rsqf((((p[0] + p[1]) + (p[2] + p[3])) + ssq_kp[row]) * (1.f / QKD) + EPS), ks = rl[ai][m] * rinv;
;                 bf16_t* kvp = KV + (size_t)row * (NH * 256) + h * 256 + colk;
;                 { const f32x4 k0 = acc[ai][0][m][0] * ks * g0, k1 = acc[ai][0][m][1] * ks * g1;
;                   u32x4 w; w.x = cvt_pk_bf16(k0[0], k0[1]); w.y = cvt_pk_bf16(k0[2], k0[3]); w.z = cvt_pk_bf16(k1[0], k1[1]); w.w = cvt_pk_bf16(k1[2], k1[3]); *(u32x4*)kvp = w; }
;                 { const f32x4 v0 = acc[ai][1][m][0] * rl[ai][m], v1 = acc[ai][1][m][1] * rl[ai][m];
;                   u32x4 w; w.x = cvt_pk_bf16(v0[0], v0[1]); w.y = cvt_pk_bf16(v0[2], v0[3]); w.z = cvt_pk_bf16(v1[0], v1[1]); w.w = cvt_pk_bf16(v1[2], v1[3]); *(u32x4*)(kvp + 128) = w; }
;                 const float* kp = QK + (size_t)row * NQKVA + (QLORA + KVLORA) + dA;
;                 const f32x2 ya = *(const f32x2*)kp * rinv * ga, yb = *(const f32x2*)(kp + 16) * rinv * gb;
;                 f32x2 cs = (f32x2){1.f, 1.f}, sn = (f32x2){0.f, 0.f};
;                 if (row < MLAT) { const int s = row & (SEQ - 1), pos = wc < 2 ? (s >> 6) : (s & 63); cs = *(const f32x2*)(rope + pos * 16 + ff); sn = *(const f32x2*)(rope + 1024 + pos * 16 + ff); }
;                 const f32x2 za = ya * cs - yb * sn, zb = yb * cs + ya * sn;
;                 bf16_t* pe = KPE + (size_t)row * (NH * QKR) + h * QKR + dA;
;                 *(unsigned*)pe = cvt_pk_bf16(za.x, za.y); *(unsigned*)(pe + 16) = cvt_pk_bf16(zb.x, zb.y); }
.LBB0_1368:
	s_or_b64 exec, exec, s[40:41]
	s_waitcnt vmcnt(0)
	v_pk_mul_f32 v[32:33], v[54:55], v[32:33] op_sel_hi:[0,1]
	v_pk_mul_f32 v[34:35], v[54:55], v[34:35] op_sel_hi:[0,1]
	v_pk_mul_f32 v[32:33], v[158:159], v[32:33]
	v_pk_mul_f32 v[34:35], v[156:157], v[34:35]
	v_pk_mul_f32 v[36:37], v[32:33], v[50:51]
	v_mov_b32_e32 v163, v162
	v_pk_fma_f32 v[36:37], v[34:35], v[48:49], v[36:37] neg_lo:[0,0,1] neg_hi:[0,0,1]
	v_pk_mul_f32 v[34:35], v[34:35], v[50:51]
	v_cvt_pk_bf16_f32 v36, v36, v37
	v_pk_mul_f32 v[20:21], v[20:21], v[162:163]
	v_pk_fma_f32 v[32:33], v[32:33], v[48:49], v[34:35]
	v_lshlrev_b64 v[34:35], 10, v[52:53]
	v_lshl_add_u64 v[34:35], s[16:17], 0, v[34:35]
	v_lshl_add_u64 v[34:35], s[38:39], 1, v[34:35]
	v_lshl_add_u64 v[34:35], v[34:35], 0, v[120:121]
	global_store_dword v[34:35], v36, off
	v_cvt_pk_bf16_f32 v32, v32, v33
	global_store_dword v[34:35], v32, off offset:32
	ds_read_b128 v[34:37], v129 offset:2560
	v_or_b32_e32 v32, 32, v72
	v_ashrrev_i32_e32 v33, 31, v32
	v_cmp_gt_i32_e32 vcc, s83, v32
	s_waitcnt lgkmcnt(0)
	v_mov_b32_e32 v38, v35
	v_mov_b32_e32 v39, v36
	v_mov_b32_e32 v35, v37
	v_pk_add_f32 v[34:35], v[38:39], v[34:35]
	v_lshlrev_b64 v[38:39], 12, v[32:33]
	v_add_f32_e32 v36, v34, v35
	v_lshl_add_u64 v[34:35], v[32:33], 2, s[20:21]
	global_load_dword v34, v[34:35], off
	v_lshl_add_u64 v[38:39], s[14:15], 0, v[38:39]
	v_lshl_add_u64 v[38:39], s[36:37], 1, v[38:39]
	v_lshl_add_u64 v[38:39], v[38:39], 0, v[172:173]
	s_waitcnt vmcnt(0)
	v_add_f32_e32 v34, v34, v36
	v_fmamk_f32 v34, v34, 0x3baaaaab, v189
	v_rsq_f32_e32 v34, v34
	s_nop 0
	v_mul_f32_e32 v36, v162, v34
	v_pk_mul_f32 v[28:29], v[28:29], v[36:37] op_sel_hi:[1,0]
	v_pk_mul_f32 v[30:31], v[30:31], v[36:37] op_sel_hi:[1,0]
	v_pk_mul_f32 v[24:25], v[24:25], v[36:37] op_sel_hi:[1,0]
	v_pk_mul_f32 v[26:27], v[26:27], v[36:37] op_sel_hi:[1,0]
	v_pk_mul_f32 v[30:31], v[70:71], v[30:31]
	v_pk_mul_f32 v[28:29], v[68:69], v[28:29]
	v_pk_mul_f32 v[36:37], v[66:67], v[26:27]
	v_pk_mul_f32 v[26:27], v[64:65], v[24:25]
	v_cvt_pk_bf16_f32 v24, v28, v29
	v_cvt_pk_bf16_f32 v25, v30, v31
	s_nop 0
	v_cvt_pk_bf16_f32 v26, v26, v27
	v_cvt_pk_bf16_f32 v27, v36, v37
	global_store_dwordx4 v[38:39], v[24:27], off
	s_nop 1
	v_mov_b32_e32 v24, v162
	v_mov_b32_e32 v25, v162
	v_pk_mul_f32 v[22:23], v[22:23], v[24:25]
	v_pk_mul_f32 v[24:25], v[18:19], v[24:25]
	v_pk_mul_f32 v[18:19], v[16:17], v[162:163]
	v_cvt_pk_bf16_f32 v16, v20, v21
	v_cvt_pk_bf16_f32 v17, v22, v23
	v_mov_b32_e32 v26, 0
	v_cvt_pk_bf16_f32 v18, v18, v19
	v_cvt_pk_bf16_f32 v19, v24, v25
	global_store_dwordx4 v[38:39], v[16:19], off offset:256
	v_mov_b32_e32 v24, 1.0
	v_mov_b32_e32 v25, 1.0
	v_mad_i64_i32 v[16:17], s[40:41], v32, s89, v[154:155]
	s_nop 2
	v_mov_b32_e32 v22, v204
	v_mov_b32_e32 v23, v205
	s_nop 2
	v_mov_b32_e32 v20, v218
	v_mov_b32_e32 v21, v219
	v_mov_b32_e32 v18, 0
	v_mov_b32_e32 v16, 1.0
	v_mov_b32_e32 v27, 0
	s_and_saveexec_b64 s[40:41], vcc
	s_cbranch_execz .LBB0_1370
	v_cndmask_b32_e64 v17, v32, v62, s[8:9]
	v_lshlrev_b32_e32 v17, 6, v17
	v_and_b32_e32 v24, 0xfc0, v17
	v_mov_b32_e32 v25, v173
	v_lshl_add_u64 v[26:27], v[146:147], 0, v[24:25]
	v_lshl_add_u64 v[28:29], v[152:153], 0, v[24:25]
	global_load_dwordx2 v[24:25], v[26:27], off
	s_nop 0
	global_load_dwordx2 v[26:27], v[28:29], off
.LBB0_1370:
	s_or_b64 exec, exec, s[40:41]
	s_waitcnt vmcnt(0)
	v_pk_mul_f32 v[20:21], v[34:35], v[20:21] op_sel_hi:[0,1]
	v_pk_mul_f32 v[22:23], v[34:35], v[22:23] op_sel_hi:[0,1]
	v_pk_mul_f32 v[20:21], v[158:159], v[20:21]
	v_pk_mul_f32 v[22:23], v[156:157], v[22:23]
	v_pk_mul_f32 v[28:29], v[20:21], v[26:27]
	v_mov_b32_e32 v121, v173
	v_pk_fma_f32 v[28:29], v[22:23], v[24:25], v[28:29] neg_lo:[0,0,1] neg_hi:[0,0,1]
	v_pk_mul_f32 v[22:23], v[22:23], v[26:27]
	v_cvt_pk_bf16_f32 v17, v28, v29
	v_mov_b32_e32 v161, v160
	v_pk_fma_f32 v[20:21], v[20:21], v[24:25], v[22:23]
	v_lshlrev_b64 v[22:23], 10, v[32:33]
	v_lshl_add_u64 v[22:23], s[16:17], 0, v[22:23]
	v_lshl_add_u64 v[22:23], s[38:39], 1, v[22:23]
	v_lshl_add_u64 v[22:23], v[22:23], 0, v[120:121]
	global_store_dword v[22:23], v17, off
	v_cvt_pk_bf16_f32 v17, v20, v21
	global_store_dword v[22:23], v17, off offset:32
	ds_read_b128 v[22:25], v129 offset:2816
	v_or_b32_e32 v20, 48, v72
	v_ashrrev_i32_e32 v21, 31, v20
	v_pk_mul_f32 v[4:5], v[4:5], v[160:161]
	v_cmp_gt_i32_e32 vcc, s83, v20
	s_waitcnt lgkmcnt(0)
	v_mov_b32_e32 v26, v23
	v_mov_b32_e32 v27, v24
	v_mov_b32_e32 v23, v25
	v_pk_add_f32 v[22:23], v[26:27], v[22:23]
	v_lshlrev_b64 v[26:27], 12, v[20:21]
	v_add_f32_e32 v17, v22, v23
	v_lshl_add_u64 v[22:23], v[20:21], 2, s[20:21]
	global_load_dword v19, v[22:23], off
	v_lshl_add_u64 v[26:27], s[14:15], 0, v[26:27]
	v_lshl_add_u64 v[26:27], s[36:37], 1, v[26:27]
	v_lshl_add_u64 v[26:27], v[26:27], 0, v[172:173]
	s_waitcnt vmcnt(0)
	v_add_f32_e32 v17, v19, v17
	v_fmamk_f32 v17, v17, 0x3baaaaab, v189
	v_rsq_f32_e32 v22, v17
	v_mov_b32_e32 v17, 1.0
	v_mov_b32_e32 v19, 0
	v_mul_f32_e32 v24, v160, v22
	v_pk_mul_f32 v[12:13], v[12:13], v[24:25] op_sel_hi:[1,0]
	v_pk_mul_f32 v[14:15], v[14:15], v[24:25] op_sel_hi:[1,0]
	v_pk_mul_f32 v[8:9], v[8:9], v[24:25] op_sel_hi:[1,0]
	v_pk_mul_f32 v[10:11], v[10:11], v[24:25] op_sel_hi:[1,0]
	v_pk_mul_f32 v[14:15], v[70:71], v[14:15]
	v_pk_mul_f32 v[12:13], v[68:69], v[12:13]
	v_pk_mul_f32 v[24:25], v[66:67], v[10:11]
	v_pk_mul_f32 v[10:11], v[64:65], v[8:9]
	v_cvt_pk_bf16_f32 v8, v12, v13
	v_cvt_pk_bf16_f32 v9, v14, v15
	s_nop 0
	v_cvt_pk_bf16_f32 v10, v10, v11
	v_cvt_pk_bf16_f32 v11, v24, v25
	global_store_dwordx4 v[26:27], v[8:11], off
	s_nop 1
	v_mov_b32_e32 v8, v160
	v_mov_b32_e32 v9, v160
	v_pk_mul_f32 v[6:7], v[6:7], v[8:9]
	v_pk_mul_f32 v[8:9], v[2:3], v[8:9]
	v_pk_mul_f32 v[2:3], v[0:1], v[160:161]
	v_cvt_pk_bf16_f32 v0, v4, v5
	v_cvt_pk_bf16_f32 v1, v6, v7
	s_nop 0
	v_cvt_pk_bf16_f32 v2, v2, v3
	v_cvt_pk_bf16_f32 v3, v8, v9
	global_store_dwordx4 v[26:27], v[0:3], off offset:256
	s_nop 1
	v_mad_i64_i32 v[2:3], s[36:37], v20, s89, v[154:155]
	s_nop 2
	v_mov_b32_e32 v0, v206
	v_mov_b32_e32 v1, v207
	s_nop 0
	s_nop 2
	v_mov_b32_e32 v2, v220
	v_mov_b32_e32 v3, v221
	s_and_saveexec_b64 s[36:37], vcc
	s_cbranch_execz .LBB0_1372
	v_cndmask_b32_e64 v4, v20, v62, s[8:9]
	v_lshlrev_b32_e32 v4, 6, v4
	v_and_b32_e32 v4, 0xfc0, v4
	v_mov_b32_e32 v5, v173
	v_lshl_add_u64 v[6:7], v[146:147], 0, v[4:5]
	v_lshl_add_u64 v[4:5], v[152:153], 0, v[4:5]
	global_load_dwordx2 v[16:17], v[6:7], off
	global_load_dwordx2 v[18:19], v[4:5], off
